# scan: LDS operand waits split per consumer (A/K at step top, W and B at first use)
# baseline (speedup 1.0000x reference)
; DI void scan_task(const Params& p, int l, int isP, int b, int h, int rg, char* smem, const bool dry) {
;     ...
;     f32x4 w4 = *(const f32x4*)fw, a4 = *(const f32x4*)fa, b4 = *(const f32x4*)fb;
;     uint2 ur = *(const uint2*)pr, uk = *(const uint2*)pk;
;     float v = vb[0];
; #pragma unroll
;     for (int s = 0; s < 32; s++) {
;       f32x4 w4n = w4, a4n = a4, b4n = b4;
;       uint2 urn = ur, ukn = uk;
;       float vn = v;
;       if (s < 31) {
;         w4n = *(const f32x4*)(fw + (s + 1) * 64);
;         a4n = *(const f32x4*)(fa + (s + 1) * 64);
;         b4n = *(const f32x4*)(fb + (s + 1) * 64);
;         urn = *(const uint2*)(pr + (s + 1) * 128);
;         ukn = *(const uint2*)(pk + (s + 1) * 128);
;         vn = vb[(s + 1) * 16];
;       }
;       __builtin_amdgcn_sched_barrier(0);
;       const f32x2 klo = {__uint_as_float(uk.x << 16), __uint_as_float(uk.x & 0xFFFF0000u)};
;       const f32x2 khi = {__uint_as_float(uk.y << 16), __uint_as_float(uk.y & 0xFFFF0000u)};
;       const f32x2 rlo = {__uint_as_float(ur.x << 16), __uint_as_float(ur.x & 0xFFFF0000u)};
;       const f32x2 rhi = {__uint_as_float(ur.y << 16), __uint_as_float(ur.y & 0xFFFF0000u)};
;       const f32x2 vv = {v, v};
;       const f32x2 t = Sa * a4.lo + Sb * a4.hi;
;       const f32x2 na = Sa * w4.lo + vv * klo;
;       const f32x2 nb = Sb * w4.hi + vv * khi;
;       float sa = t.x + t.y;
;       float yp = yprev;
;       rowsum16x2(sa, yp);
;       if (s >= 1 && s <= 16) ykeep0 = (jq == s - 1) ? yp : ykeep0;
;       if (s >= 17) ykeep1 = (jq == s - 17) ? yp : ykeep1;
;       const f32x2 sv = {sa, sa};
;       Sa = na + sv * b4.lo;
;       Sb = nb + sv * b4.hi;
;       const f32x2 yy = Sa * rlo + Sb * rhi;
;       yprev = yy.x + yy.y;
;       w4 = w4n; a4 = a4n; b4 = b4n; ur = urn; uk = ukn; v = vn;
;     }
.Lscan_noldA:
	s_waitcnt lgkmcnt(8)
	v_pk_mul_f32 v[56:57], v[4:5], v[12:13]
	v_pk_fma_f32 v[56:57], v[6:7], v[14:15], v[56:57]
	ds_read_b128 v[12:15], v76 offset:4608
	v_add_f32_e32 v58, v56, v57
	v_pk_mul_f32 v[60:61], v[48:49], v[24:25] op_sel_hi:[0,1]
	v_pk_mul_f32 v[62:63], v[48:49], v[26:27] op_sel_hi:[0,1]
	v_add_f32_dpp v58, v58, v58 quad_perm:[1,0,3,2] row_mask:0xf bank_mask:0xf bound_ctrl:1
	ds_read_b128 v[24:27], v76 offset:16896
	s_nop 0
	v_add_f32_dpp v58, v58, v58 quad_perm:[2,3,0,1] row_mask:0xf bank_mask:0xf bound_ctrl:1
	s_waitcnt lgkmcnt(9)
	v_pk_fma_f32 v[60:61], v[4:5], v[8:9], v[60:61]
	v_pk_fma_f32 v[62:63], v[6:7], v[10:11], v[62:63]
	v_add_f32_dpp v58, v58, v58 row_half_mirror row_mask:0xf bank_mask:0xf bound_ctrl:1
	ds_read_b128 v[8:11], v76 offset:512
	s_nop 0
	v_add_f32_dpp v58, v58, v58 row_mirror row_mask:0xf bank_mask:0xf bound_ctrl:1
	s_waitcnt lgkmcnt(9)
	v_pk_fma_f32 v[4:5], v[58:59], v[16:17], v[60:61] op_sel_hi:[0,1,1]
	v_pk_fma_f32 v[6:7], v[58:59], v[18:19], v[62:63] op_sel_hi:[0,1,1]
	ds_read_b128 v[16:19], v76 offset:8704
	s_waitcnt lgkmcnt(7)
	v_pk_mul_f32 v[56:57], v[4:5], v[32:33]
	v_pk_mul_f32 v[64:65], v[4:5], v[20:21]
	v_pk_fma_f32 v[56:57], v[6:7], v[34:35], v[56:57]
	ds_read_b128 v[32:35], v76 offset:4864
	v_pk_fma_f32 v[64:65], v[6:7], v[22:23], v[64:65]
	ds_read_b128 v[20:23], v76 offset:12800
	v_add_f32_e32 v58, v56, v57
	v_pk_mul_f32 v[60:61], v[48:49], v[44:45] op_sel:[1,0] op_sel_hi:[1,1]
	v_pk_mul_f32 v[62:63], v[48:49], v[46:47] op_sel:[1,0] op_sel_hi:[1,1]
	v_add_f32_dpp v58, v58, v58 quad_perm:[1,0,3,2] row_mask:0xf bank_mask:0xf bound_ctrl:1
	ds_read_b128 v[44:47], v76 offset:17152
	v_add_f32_e32 v66, v64, v65
	ds_read_b128 v[52:55], v77 offset:20496
	v_add_f32_dpp v58, v58, v58 quad_perm:[2,3,0,1] row_mask:0xf bank_mask:0xf bound_ctrl:1
	s_waitcnt lgkmcnt(10)
	v_pk_fma_f32 v[60:61], v[4:5], v[28:29], v[60:61]
	v_pk_fma_f32 v[62:63], v[6:7], v[30:31], v[62:63]
	v_add_f32_dpp v58, v58, v58 row_half_mirror row_mask:0xf bank_mask:0xf bound_ctrl:1
	ds_read_b128 v[28:31], v76 offset:768
	s_nop 0
	v_add_f32_dpp v58, v58, v58 row_mirror row_mask:0xf bank_mask:0xf bound_ctrl:1
	s_waitcnt lgkmcnt(10)
	v_pk_fma_f32 v[4:5], v[58:59], v[36:37], v[60:61] op_sel_hi:[0,1,1]
	v_pk_fma_f32 v[6:7], v[58:59], v[38:39], v[62:63] op_sel_hi:[0,1,1]
	ds_read_b128 v[36:39], v76 offset:8960
	s_waitcnt lgkmcnt(8)
	v_pk_mul_f32 v[56:57], v[4:5], v[12:13]
	v_pk_mul_f32 v[64:65], v[4:5], v[40:41]
	v_pk_fma_f32 v[56:57], v[6:7], v[14:15], v[56:57]
	ds_read_b128 v[12:15], v76 offset:5120
	v_pk_fma_f32 v[64:65], v[6:7], v[42:43], v[64:65]
	ds_read_b128 v[40:43], v76 offset:13056
	v_add_f32_e32 v58, v56, v57
	v_pk_mul_f32 v[60:61], v[50:51], v[24:25] op_sel_hi:[0,1]
	v_pk_mul_f32 v[62:63], v[50:51], v[26:27] op_sel_hi:[0,1]
	v_add_f32_dpp v58, v58, v58 quad_perm:[1,0,3,2] row_mask:0xf bank_mask:0xf bound_ctrl:1
	ds_read_b128 v[24:27], v76 offset:17408
	v_add_f32_e32 v67, v64, v65
	v_add_f32_dpp v58, v58, v58 quad_perm:[2,3,0,1] row_mask:0xf bank_mask:0xf bound_ctrl:1
	s_waitcnt lgkmcnt(10)
	v_pk_fma_f32 v[60:61], v[4:5], v[8:9], v[60:61]
	v_pk_fma_f32 v[62:63], v[6:7], v[10:11], v[62:63]
	v_add_f32_dpp v68, v66, v66 row_mirror row_mask:0xf bank_mask:0x3
	v_add_f32_dpp v58, v58, v58 row_half_mirror row_mask:0xf bank_mask:0xf bound_ctrl:1
	ds_read_b128 v[8:11], v76 offset:1024
	v_add_f32_dpp v68, v67, v67 row_mirror row_mask:0xf bank_mask:0xc
	v_add_f32_dpp v58, v58, v58 row_mirror row_mask:0xf bank_mask:0xf bound_ctrl:1
	s_waitcnt lgkmcnt(10)
	v_pk_fma_f32 v[4:5], v[58:59], v[16:17], v[60:61] op_sel_hi:[0,1,1]
	v_pk_fma_f32 v[6:7], v[58:59], v[18:19], v[62:63] op_sel_hi:[0,1,1]
	ds_read_b128 v[16:19], v76 offset:9216
	s_waitcnt lgkmcnt(8)
	v_pk_mul_f32 v[56:57], v[4:5], v[32:33]
	v_pk_mul_f32 v[64:65], v[4:5], v[20:21]
	v_pk_fma_f32 v[56:57], v[6:7], v[34:35], v[56:57]
	ds_read_b128 v[32:35], v76 offset:5376
	v_pk_fma_f32 v[64:65], v[6:7], v[22:23], v[64:65]
	ds_read_b128 v[20:23], v76 offset:13312
	v_add_f32_e32 v58, v56, v57
	v_pk_mul_f32 v[60:61], v[50:51], v[44:45] op_sel:[1,0] op_sel_hi:[1,1]
	v_pk_mul_f32 v[62:63], v[50:51], v[46:47] op_sel:[1,0] op_sel_hi:[1,1]
	v_add_f32_dpp v58, v58, v58 quad_perm:[1,0,3,2] row_mask:0xf bank_mask:0xf bound_ctrl:1
	ds_read_b128 v[44:47], v76 offset:17664
	v_add_f32_e32 v66, v64, v65
	v_add_f32_dpp v58, v58, v58 quad_perm:[2,3,0,1] row_mask:0xf bank_mask:0xf bound_ctrl:1
	s_waitcnt lgkmcnt(9)
	v_pk_fma_f32 v[60:61], v[4:5], v[28:29], v[60:61]
	v_pk_fma_f32 v[62:63], v[6:7], v[30:31], v[62:63]
	v_add_f32_dpp v58, v58, v58 row_half_mirror row_mask:0xf bank_mask:0xf bound_ctrl:1
	ds_read_b128 v[28:31], v76 offset:1280
	s_nop 0
	v_add_f32_dpp v58, v58, v58 row_mirror row_mask:0xf bank_mask:0xf bound_ctrl:1
	s_waitcnt lgkmcnt(9)
	v_pk_fma_f32 v[4:5], v[58:59], v[36:37], v[60:61] op_sel_hi:[0,1,1]
	v_pk_fma_f32 v[6:7], v[58:59], v[38:39], v[62:63] op_sel_hi:[0,1,1]
	ds_read_b128 v[36:39], v76 offset:9472
	s_waitcnt lgkmcnt(7)
	v_pk_mul_f32 v[56:57], v[4:5], v[12:13]
	v_pk_mul_f32 v[64:65], v[4:5], v[40:41]
	v_pk_fma_f32 v[56:57], v[6:7], v[14:15], v[56:57]
	ds_read_b128 v[12:15], v76 offset:5632
	v_pk_fma_f32 v[64:65], v[6:7], v[42:43], v[64:65]
	ds_read_b128 v[40:43], v76 offset:13568
	v_add_f32_e32 v58, v56, v57
	v_pk_mul_f32 v[60:61], v[52:53], v[24:25] op_sel_hi:[0,1]
	v_pk_mul_f32 v[62:63], v[52:53], v[26:27] op_sel_hi:[0,1]
	v_add_f32_dpp v58, v58, v58 quad_perm:[1,0,3,2] row_mask:0xf bank_mask:0xf bound_ctrl:1
	ds_read_b128 v[24:27], v76 offset:17920
	v_add_f32_e32 v67, v64, v65
	v_add_f32_dpp v58, v58, v58 quad_perm:[2,3,0,1] row_mask:0xf bank_mask:0xf bound_ctrl:1
	s_waitcnt lgkmcnt(9)
; DI void scan_task(const Params& p, int l, int isP, int b, int h, int rg, char* smem, const bool dry) {
;     ...
; #pragma unroll
;     for (int s = 0; s < 32; s++) {
;       f32x4 w4n = w4, a4n = a4, b4n = b4;
;       uint2 urn = ur, ukn = uk;
;       float vn = v;
;       if (s < 31) {
;         w4n = *(const f32x4*)(fw + (s + 1) * 64);
;         a4n = *(const f32x4*)(fa + (s + 1) * 64);
;         b4n = *(const f32x4*)(fb + (s + 1) * 64);
;         urn = *(const uint2*)(pr + (s + 1) * 128);
;         ukn = *(const uint2*)(pk + (s + 1) * 128);
;         vn = vb[(s + 1) * 16];
;       }
;       __builtin_amdgcn_sched_barrier(0);
;       const f32x2 klo = {__uint_as_float(uk.x << 16), __uint_as_float(uk.x & 0xFFFF0000u)};
;       const f32x2 khi = {__uint_as_float(uk.y << 16), __uint_as_float(uk.y & 0xFFFF0000u)};
;       const f32x2 rlo = {__uint_as_float(ur.x << 16), __uint_as_float(ur.x & 0xFFFF0000u)};
;       const f32x2 rhi = {__uint_as_float(ur.y << 16), __uint_as_float(ur.y & 0xFFFF0000u)};
;       const f32x2 vv = {v, v};
;       const f32x2 t = Sa * a4.lo + Sb * a4.hi;
;       const f32x2 na = Sa * w4.lo + vv * klo;
;       const f32x2 nb = Sb * w4.hi + vv * khi;
;       float sa = t.x + t.y;
;       float yp = yprev;
;       rowsum16x2(sa, yp);
;       if (s >= 1 && s <= 16) ykeep0 = (jq == s - 1) ? yp : ykeep0;
;       if (s >= 17) ykeep1 = (jq == s - 17) ? yp : ykeep1;
;       const f32x2 sv = {sa, sa};
;       Sa = na + sv * b4.lo;
;       Sb = nb + sv * b4.hi;
;       const f32x2 yy = Sa * rlo + Sb * rhi;
;       yprev = yy.x + yy.y;
;       w4 = w4n; a4 = a4n; b4 = b4n; ur = urn; uk = ukn; v = vn;
;     }
	v_pk_fma_f32 v[60:61], v[4:5], v[8:9], v[60:61]
	v_pk_fma_f32 v[62:63], v[6:7], v[10:11], v[62:63]
	v_add_f32_dpp v69, v66, v66 row_mirror row_mask:0xf bank_mask:0x3
	v_add_f32_dpp v58, v58, v58 row_half_mirror row_mask:0xf bank_mask:0xf bound_ctrl:1
	ds_read_b128 v[8:11], v76 offset:1536
	v_add_f32_dpp v69, v67, v67 row_mirror row_mask:0xf bank_mask:0xc
	v_add_f32_dpp v58, v58, v58 row_mirror row_mask:0xf bank_mask:0xf bound_ctrl:1
	s_waitcnt lgkmcnt(9)
	v_pk_fma_f32 v[4:5], v[58:59], v[16:17], v[60:61] op_sel_hi:[0,1,1]
	v_pk_fma_f32 v[6:7], v[58:59], v[18:19], v[62:63] op_sel_hi:[0,1,1]
	ds_read_b128 v[16:19], v76 offset:9728
	s_waitcnt lgkmcnt(7)
	v_pk_mul_f32 v[56:57], v[4:5], v[32:33]
	v_pk_mul_f32 v[64:65], v[4:5], v[20:21]
	v_pk_fma_f32 v[56:57], v[6:7], v[34:35], v[56:57]
	ds_read_b128 v[32:35], v76 offset:5888
	v_pk_fma_f32 v[64:65], v[6:7], v[22:23], v[64:65]
	ds_read_b128 v[20:23], v76 offset:13824
	v_add_f32_e32 v58, v56, v57
	v_pk_mul_f32 v[60:61], v[52:53], v[44:45] op_sel:[1,0] op_sel_hi:[1,1]
	v_pk_mul_f32 v[62:63], v[52:53], v[46:47] op_sel:[1,0] op_sel_hi:[1,1]
	v_add_f32_dpp v58, v58, v58 quad_perm:[1,0,3,2] row_mask:0xf bank_mask:0xf bound_ctrl:1
	ds_read_b128 v[44:47], v76 offset:18176
	v_add_f32_e32 v66, v64, v65
	ds_read_b128 v[48:51], v77 offset:20512
	v_add_f32_dpp v58, v58, v58 quad_perm:[2,3,0,1] row_mask:0xf bank_mask:0xf bound_ctrl:1
	s_waitcnt lgkmcnt(10)
	v_pk_fma_f32 v[60:61], v[4:5], v[28:29], v[60:61]
	v_pk_fma_f32 v[62:63], v[6:7], v[30:31], v[62:63]
	v_add_f32_dpp v68, v68, v68 row_half_mirror row_mask:0xf bank_mask:0x5
	v_add_f32_dpp v58, v58, v58 row_half_mirror row_mask:0xf bank_mask:0xf bound_ctrl:1
	ds_read_b128 v[28:31], v76 offset:1792
	v_add_f32_dpp v68, v69, v69 row_half_mirror row_mask:0xf bank_mask:0xa
	v_add_f32_dpp v58, v58, v58 row_mirror row_mask:0xf bank_mask:0xf bound_ctrl:1
	s_waitcnt lgkmcnt(10)
	v_pk_fma_f32 v[4:5], v[58:59], v[36:37], v[60:61] op_sel_hi:[0,1,1]
	v_pk_fma_f32 v[6:7], v[58:59], v[38:39], v[62:63] op_sel_hi:[0,1,1]
	ds_read_b128 v[36:39], v76 offset:9984
	s_waitcnt lgkmcnt(8)
	v_pk_mul_f32 v[56:57], v[4:5], v[12:13]
	v_pk_mul_f32 v[64:65], v[4:5], v[40:41]
	v_pk_fma_f32 v[56:57], v[6:7], v[14:15], v[56:57]
	ds_read_b128 v[12:15], v76 offset:6144
	v_pk_fma_f32 v[64:65], v[6:7], v[42:43], v[64:65]
	ds_read_b128 v[40:43], v76 offset:14080
	v_add_f32_e32 v58, v56, v57
	v_pk_mul_f32 v[60:61], v[54:55], v[24:25] op_sel_hi:[0,1]
	v_pk_mul_f32 v[62:63], v[54:55], v[26:27] op_sel_hi:[0,1]
	v_add_f32_dpp v58, v58, v58 quad_perm:[1,0,3,2] row_mask:0xf bank_mask:0xf bound_ctrl:1
	ds_read_b128 v[24:27], v76 offset:18432
	v_add_f32_e32 v67, v64, v65
	v_add_f32_dpp v58, v58, v58 quad_perm:[2,3,0,1] row_mask:0xf bank_mask:0xf bound_ctrl:1
	s_waitcnt lgkmcnt(10)
	v_pk_fma_f32 v[60:61], v[4:5], v[8:9], v[60:61]
	v_pk_fma_f32 v[62:63], v[6:7], v[10:11], v[62:63]
	v_add_f32_dpp v70, v66, v66 row_mirror row_mask:0xf bank_mask:0x3
	v_add_f32_dpp v58, v58, v58 row_half_mirror row_mask:0xf bank_mask:0xf bound_ctrl:1
	ds_read_b128 v[8:11], v76 offset:2048
	v_add_f32_dpp v70, v67, v67 row_mirror row_mask:0xf bank_mask:0xc
	v_add_f32_dpp v58, v58, v58 row_mirror row_mask:0xf bank_mask:0xf bound_ctrl:1
	s_waitcnt lgkmcnt(10)
	v_pk_fma_f32 v[4:5], v[58:59], v[16:17], v[60:61] op_sel_hi:[0,1,1]
	v_pk_fma_f32 v[6:7], v[58:59], v[18:19], v[62:63] op_sel_hi:[0,1,1]
	ds_read_b128 v[16:19], v76 offset:10240
	s_waitcnt lgkmcnt(8)
	v_pk_mul_f32 v[56:57], v[4:5], v[32:33]
	v_pk_mul_f32 v[64:65], v[4:5], v[20:21]
	v_pk_fma_f32 v[56:57], v[6:7], v[34:35], v[56:57]
	ds_read_b128 v[32:35], v76 offset:6400
	v_pk_fma_f32 v[64:65], v[6:7], v[22:23], v[64:65]
	ds_read_b128 v[20:23], v76 offset:14336
	v_add_f32_e32 v58, v56, v57
	v_pk_mul_f32 v[60:61], v[54:55], v[44:45] op_sel:[1,0] op_sel_hi:[1,1]
	v_pk_mul_f32 v[62:63], v[54:55], v[46:47] op_sel:[1,0] op_sel_hi:[1,1]
	v_add_f32_dpp v58, v58, v58 quad_perm:[1,0,3,2] row_mask:0xf bank_mask:0xf bound_ctrl:1
	ds_read_b128 v[44:47], v76 offset:18688
	v_add_f32_e32 v66, v64, v65
	v_add_f32_dpp v58, v58, v58 quad_perm:[2,3,0,1] row_mask:0xf bank_mask:0xf bound_ctrl:1
	s_waitcnt lgkmcnt(9)
	v_pk_fma_f32 v[60:61], v[4:5], v[28:29], v[60:61]
	v_pk_fma_f32 v[62:63], v[6:7], v[30:31], v[62:63]
	v_add_f32_dpp v58, v58, v58 row_half_mirror row_mask:0xf bank_mask:0xf bound_ctrl:1
	ds_read_b128 v[28:31], v76 offset:2304
	s_nop 0
	v_add_f32_dpp v58, v58, v58 row_mirror row_mask:0xf bank_mask:0xf bound_ctrl:1
	s_waitcnt lgkmcnt(9)
	v_pk_fma_f32 v[4:5], v[58:59], v[36:37], v[60:61] op_sel_hi:[0,1,1]
	v_pk_fma_f32 v[6:7], v[58:59], v[38:39], v[62:63] op_sel_hi:[0,1,1]
	ds_read_b128 v[36:39], v76 offset:10496
	s_waitcnt lgkmcnt(7)
	v_pk_mul_f32 v[56:57], v[4:5], v[12:13]
	v_pk_mul_f32 v[64:65], v[4:5], v[40:41]
	v_pk_fma_f32 v[56:57], v[6:7], v[14:15], v[56:57]
	ds_read_b128 v[12:15], v76 offset:6656
	v_pk_fma_f32 v[64:65], v[6:7], v[42:43], v[64:65]
	ds_read_b128 v[40:43], v76 offset:14592
	v_add_f32_e32 v58, v56, v57
	v_pk_mul_f32 v[60:61], v[48:49], v[24:25] op_sel_hi:[0,1]
	v_pk_mul_f32 v[62:63], v[48:49], v[26:27] op_sel_hi:[0,1]
	v_add_f32_dpp v58, v58, v58 quad_perm:[1,0,3,2] row_mask:0xf bank_mask:0xf bound_ctrl:1
	ds_read_b128 v[24:27], v76 offset:18944
	v_add_f32_e32 v67, v64, v65
	v_add_f32_dpp v58, v58, v58 quad_perm:[2,3,0,1] row_mask:0xf bank_mask:0xf bound_ctrl:1
	s_waitcnt lgkmcnt(9)
	v_pk_fma_f32 v[60:61], v[4:5], v[8:9], v[60:61]
	v_pk_fma_f32 v[62:63], v[6:7], v[10:11], v[62:63]
	v_add_f32_dpp v71, v66, v66 row_mirror row_mask:0xf bank_mask:0x3
	v_add_f32_dpp v58, v58, v58 row_half_mirror row_mask:0xf bank_mask:0xf bound_ctrl:1
	ds_read_b128 v[8:11], v76 offset:2560
	v_add_f32_dpp v71, v67, v67 row_mirror row_mask:0xf bank_mask:0xc
	v_add_f32_dpp v58, v58, v58 row_mirror row_mask:0xf bank_mask:0xf bound_ctrl:1
	s_waitcnt lgkmcnt(9)
; DI void scan_task(const Params& p, int l, int isP, int b, int h, int rg, char* smem, const bool dry) {
;     ...
; #pragma unroll
;     for (int s = 0; s < 32; s++) {
;       f32x4 w4n = w4, a4n = a4, b4n = b4;
;       uint2 urn = ur, ukn = uk;
;       float vn = v;
;       if (s < 31) {
;         w4n = *(const f32x4*)(fw + (s + 1) * 64);
;         a4n = *(const f32x4*)(fa + (s + 1) * 64);
;         b4n = *(const f32x4*)(fb + (s + 1) * 64);
;         urn = *(const uint2*)(pr + (s + 1) * 128);
;         ukn = *(const uint2*)(pk + (s + 1) * 128);
;         vn = vb[(s + 1) * 16];
;       }
;       __builtin_amdgcn_sched_barrier(0);
;       const f32x2 klo = {__uint_as_float(uk.x << 16), __uint_as_float(uk.x & 0xFFFF0000u)};
;       const f32x2 khi = {__uint_as_float(uk.y << 16), __uint_as_float(uk.y & 0xFFFF0000u)};
;       const f32x2 rlo = {__uint_as_float(ur.x << 16), __uint_as_float(ur.x & 0xFFFF0000u)};
;       const f32x2 rhi = {__uint_as_float(ur.y << 16), __uint_as_float(ur.y & 0xFFFF0000u)};
;       const f32x2 vv = {v, v};
;       const f32x2 t = Sa * a4.lo + Sb * a4.hi;
;       const f32x2 na = Sa * w4.lo + vv * klo;
;       const f32x2 nb = Sb * w4.hi + vv * khi;
;       float sa = t.x + t.y;
;       float yp = yprev;
;       rowsum16x2(sa, yp);
;       if (s >= 1 && s <= 16) ykeep0 = (jq == s - 1) ? yp : ykeep0;
;       if (s >= 17) ykeep1 = (jq == s - 17) ? yp : ykeep1;
;       const f32x2 sv = {sa, sa};
;       Sa = na + sv * b4.lo;
;       Sb = nb + sv * b4.hi;
;       const f32x2 yy = Sa * rlo + Sb * rhi;
;       yprev = yy.x + yy.y;
;       w4 = w4n; a4 = a4n; b4 = b4n; ur = urn; uk = ukn; v = vn;
;     }
	v_pk_fma_f32 v[4:5], v[58:59], v[16:17], v[60:61] op_sel_hi:[0,1,1]
	v_pk_fma_f32 v[6:7], v[58:59], v[18:19], v[62:63] op_sel_hi:[0,1,1]
	ds_read_b128 v[16:19], v76 offset:10752
	s_waitcnt lgkmcnt(7)
	v_pk_mul_f32 v[56:57], v[4:5], v[32:33]
	v_pk_mul_f32 v[64:65], v[4:5], v[20:21]
	v_pk_fma_f32 v[56:57], v[6:7], v[34:35], v[56:57]
	ds_read_b128 v[32:35], v76 offset:6912
	v_pk_fma_f32 v[64:65], v[6:7], v[22:23], v[64:65]
	ds_read_b128 v[20:23], v76 offset:14848
	v_add_f32_e32 v58, v56, v57
	v_pk_mul_f32 v[60:61], v[48:49], v[44:45] op_sel:[1,0] op_sel_hi:[1,1]
	v_pk_mul_f32 v[62:63], v[48:49], v[46:47] op_sel:[1,0] op_sel_hi:[1,1]
	v_add_f32_dpp v58, v58, v58 quad_perm:[1,0,3,2] row_mask:0xf bank_mask:0xf bound_ctrl:1
	ds_read_b128 v[44:47], v76 offset:19200
	v_add_f32_e32 v66, v64, v65
	ds_read_b128 v[52:55], v77 offset:20528
	v_add_f32_dpp v58, v58, v58 quad_perm:[2,3,0,1] row_mask:0xf bank_mask:0xf bound_ctrl:1
	s_waitcnt lgkmcnt(10)
	v_pk_fma_f32 v[60:61], v[4:5], v[28:29], v[60:61]
	v_pk_fma_f32 v[62:63], v[6:7], v[30:31], v[62:63]
	v_add_f32_dpp v70, v70, v70 row_half_mirror row_mask:0xf bank_mask:0x5
	v_add_f32_dpp v58, v58, v58 row_half_mirror row_mask:0xf bank_mask:0xf bound_ctrl:1
	ds_read_b128 v[28:31], v76 offset:2816
	v_add_f32_dpp v70, v71, v71 row_half_mirror row_mask:0xf bank_mask:0xa
	v_add_f32_dpp v58, v58, v58 row_mirror row_mask:0xf bank_mask:0xf bound_ctrl:1
	s_waitcnt lgkmcnt(10)
	v_pk_fma_f32 v[4:5], v[58:59], v[36:37], v[60:61] op_sel_hi:[0,1,1]
	v_pk_fma_f32 v[6:7], v[58:59], v[38:39], v[62:63] op_sel_hi:[0,1,1]
	ds_read_b128 v[36:39], v76 offset:11008
	s_waitcnt lgkmcnt(8)
	v_pk_mul_f32 v[56:57], v[4:5], v[12:13]
	v_pk_mul_f32 v[64:65], v[4:5], v[40:41]
	v_pk_fma_f32 v[56:57], v[6:7], v[14:15], v[56:57]
	ds_read_b128 v[12:15], v76 offset:7168
	v_pk_fma_f32 v[64:65], v[6:7], v[42:43], v[64:65]
	ds_read_b128 v[40:43], v76 offset:15104
	v_add_f32_e32 v58, v56, v57
	v_pk_mul_f32 v[60:61], v[50:51], v[24:25] op_sel_hi:[0,1]
	v_pk_mul_f32 v[62:63], v[50:51], v[26:27] op_sel_hi:[0,1]
	v_add_f32_dpp v58, v58, v58 quad_perm:[1,0,3,2] row_mask:0xf bank_mask:0xf bound_ctrl:1
	ds_read_b128 v[24:27], v76 offset:19456
	v_add_f32_e32 v67, v64, v65
	v_add_f32_dpp v58, v58, v58 quad_perm:[2,3,0,1] row_mask:0xf bank_mask:0xf bound_ctrl:1
	s_waitcnt lgkmcnt(10)
	v_pk_fma_f32 v[60:61], v[4:5], v[8:9], v[60:61]
	v_pk_fma_f32 v[62:63], v[6:7], v[10:11], v[62:63]
	v_add_f32_dpp v72, v66, v66 row_mirror row_mask:0xf bank_mask:0x3
	v_add_f32_dpp v58, v58, v58 row_half_mirror row_mask:0xf bank_mask:0xf bound_ctrl:1
	ds_read_b128 v[8:11], v76 offset:3072
	v_add_f32_dpp v72, v67, v67 row_mirror row_mask:0xf bank_mask:0xc
	v_add_f32_dpp v58, v58, v58 row_mirror row_mask:0xf bank_mask:0xf bound_ctrl:1
	s_waitcnt lgkmcnt(10)
	v_pk_fma_f32 v[4:5], v[58:59], v[16:17], v[60:61] op_sel_hi:[0,1,1]
	v_pk_fma_f32 v[6:7], v[58:59], v[18:19], v[62:63] op_sel_hi:[0,1,1]
	ds_read_b128 v[16:19], v76 offset:11264
	s_waitcnt lgkmcnt(8)
	v_pk_mul_f32 v[56:57], v[4:5], v[32:33]
	v_pk_mul_f32 v[64:65], v[4:5], v[20:21]
	v_pk_fma_f32 v[56:57], v[6:7], v[34:35], v[56:57]
	ds_read_b128 v[32:35], v76 offset:7424
	v_pk_fma_f32 v[64:65], v[6:7], v[22:23], v[64:65]
	ds_read_b128 v[20:23], v76 offset:15360
	v_add_f32_e32 v58, v56, v57
	v_pk_mul_f32 v[60:61], v[50:51], v[44:45] op_sel:[1,0] op_sel_hi:[1,1]
	v_pk_mul_f32 v[62:63], v[50:51], v[46:47] op_sel:[1,0] op_sel_hi:[1,1]
	v_add_f32_dpp v58, v58, v58 quad_perm:[1,0,3,2] row_mask:0xf bank_mask:0xf bound_ctrl:1
	ds_read_b128 v[44:47], v76 offset:19712
	v_add_f32_e32 v66, v64, v65
	v_add_f32_dpp v58, v58, v58 quad_perm:[2,3,0,1] row_mask:0xf bank_mask:0xf bound_ctrl:1
	s_waitcnt lgkmcnt(9)
	v_pk_fma_f32 v[60:61], v[4:5], v[28:29], v[60:61]
	v_pk_fma_f32 v[62:63], v[6:7], v[30:31], v[62:63]
	v_add_f32_dpp v58, v58, v58 row_half_mirror row_mask:0xf bank_mask:0xf bound_ctrl:1
	ds_read_b128 v[28:31], v76 offset:3328
	s_nop 0
	v_add_f32_dpp v58, v58, v58 row_mirror row_mask:0xf bank_mask:0xf bound_ctrl:1
	s_waitcnt lgkmcnt(9)
	v_pk_fma_f32 v[4:5], v[58:59], v[36:37], v[60:61] op_sel_hi:[0,1,1]
	v_pk_fma_f32 v[6:7], v[58:59], v[38:39], v[62:63] op_sel_hi:[0,1,1]
	ds_read_b128 v[36:39], v76 offset:11520
	s_waitcnt lgkmcnt(7)
	v_pk_mul_f32 v[56:57], v[4:5], v[12:13]
	v_pk_mul_f32 v[64:65], v[4:5], v[40:41]
	v_pk_fma_f32 v[56:57], v[6:7], v[14:15], v[56:57]
	ds_read_b128 v[12:15], v76 offset:7680
	v_pk_fma_f32 v[64:65], v[6:7], v[42:43], v[64:65]
	ds_read_b128 v[40:43], v76 offset:15616
	v_add_f32_e32 v58, v56, v57
	v_pk_mul_f32 v[60:61], v[52:53], v[24:25] op_sel_hi:[0,1]
	v_pk_mul_f32 v[62:63], v[52:53], v[26:27] op_sel_hi:[0,1]
	v_add_f32_dpp v58, v58, v58 quad_perm:[1,0,3,2] row_mask:0xf bank_mask:0xf bound_ctrl:1
	ds_read_b128 v[24:27], v76 offset:19968
	v_add_f32_e32 v67, v64, v65
	v_add_f32_dpp v58, v58, v58 quad_perm:[2,3,0,1] row_mask:0xf bank_mask:0xf bound_ctrl:1
	s_waitcnt lgkmcnt(9)
; DI void scan_task(const Params& p, int l, int isP, int b, int h, int rg, char* smem, const bool dry) {
;     ...
; #pragma unroll
;     for (int s = 0; s < 32; s++) {
;       f32x4 w4n = w4, a4n = a4, b4n = b4;
;       uint2 urn = ur, ukn = uk;
;       float vn = v;
;       if (s < 31) {
;         w4n = *(const f32x4*)(fw + (s + 1) * 64);
;         a4n = *(const f32x4*)(fa + (s + 1) * 64);
;         b4n = *(const f32x4*)(fb + (s + 1) * 64);
;         urn = *(const uint2*)(pr + (s + 1) * 128);
;         ukn = *(const uint2*)(pk + (s + 1) * 128);
;         vn = vb[(s + 1) * 16];
;       }
;       __builtin_amdgcn_sched_barrier(0);
;       const f32x2 klo = {__uint_as_float(uk.x << 16), __uint_as_float(uk.x & 0xFFFF0000u)};
;       const f32x2 khi = {__uint_as_float(uk.y << 16), __uint_as_float(uk.y & 0xFFFF0000u)};
;       const f32x2 rlo = {__uint_as_float(ur.x << 16), __uint_as_float(ur.x & 0xFFFF0000u)};
;       const f32x2 rhi = {__uint_as_float(ur.y << 16), __uint_as_float(ur.y & 0xFFFF0000u)};
;       const f32x2 vv = {v, v};
;       const f32x2 t = Sa * a4.lo + Sb * a4.hi;
;       const f32x2 na = Sa * w4.lo + vv * klo;
;       const f32x2 nb = Sb * w4.hi + vv * khi;
;       float sa = t.x + t.y;
;       float yp = yprev;
;       rowsum16x2(sa, yp);
;       if (s >= 1 && s <= 16) ykeep0 = (jq == s - 1) ? yp : ykeep0;
;       if (s >= 17) ykeep1 = (jq == s - 17) ? yp : ykeep1;
;       const f32x2 sv = {sa, sa};
;       Sa = na + sv * b4.lo;
;       Sb = nb + sv * b4.hi;
;       const f32x2 yy = Sa * rlo + Sb * rhi;
;       yprev = yy.x + yy.y;
;       w4 = w4n; a4 = a4n; b4 = b4n; ur = urn; uk = ukn; v = vn;
;     }
	v_pk_fma_f32 v[60:61], v[4:5], v[8:9], v[60:61]
	v_pk_fma_f32 v[62:63], v[6:7], v[10:11], v[62:63]
	v_add_f32_dpp v73, v66, v66 row_mirror row_mask:0xf bank_mask:0x3
	v_add_f32_dpp v58, v58, v58 row_half_mirror row_mask:0xf bank_mask:0xf bound_ctrl:1
	ds_read_b128 v[8:11], v76 offset:3584
	v_add_f32_dpp v73, v67, v67 row_mirror row_mask:0xf bank_mask:0xc
	v_add_f32_dpp v58, v58, v58 row_mirror row_mask:0xf bank_mask:0xf bound_ctrl:1
	s_waitcnt lgkmcnt(9)
	v_pk_fma_f32 v[4:5], v[58:59], v[16:17], v[60:61] op_sel_hi:[0,1,1]
	v_pk_fma_f32 v[6:7], v[58:59], v[18:19], v[62:63] op_sel_hi:[0,1,1]
	ds_read_b128 v[16:19], v76 offset:11776
	s_waitcnt lgkmcnt(7)
	v_pk_mul_f32 v[56:57], v[4:5], v[32:33]
	v_pk_mul_f32 v[64:65], v[4:5], v[20:21]
	v_pk_fma_f32 v[56:57], v[6:7], v[34:35], v[56:57]
	ds_read_b128 v[32:35], v76 offset:7936
	v_pk_fma_f32 v[64:65], v[6:7], v[22:23], v[64:65]
	ds_read_b128 v[20:23], v76 offset:15872
	v_add_f32_e32 v58, v56, v57
	v_pk_mul_f32 v[60:61], v[52:53], v[44:45] op_sel:[1,0] op_sel_hi:[1,1]
	v_pk_mul_f32 v[62:63], v[52:53], v[46:47] op_sel:[1,0] op_sel_hi:[1,1]
	v_add_f32_dpp v58, v58, v58 quad_perm:[1,0,3,2] row_mask:0xf bank_mask:0xf bound_ctrl:1
	ds_read_b128 v[44:47], v76 offset:20224
	v_add_f32_e32 v66, v64, v65
	v_add_f32_dpp v58, v58, v58 quad_perm:[2,3,0,1] row_mask:0xf bank_mask:0xf bound_ctrl:1
	s_waitcnt lgkmcnt(9)
	v_pk_fma_f32 v[60:61], v[4:5], v[28:29], v[60:61]
	v_pk_fma_f32 v[62:63], v[6:7], v[30:31], v[62:63]
	v_add_f32_dpp v72, v72, v72 row_half_mirror row_mask:0xf bank_mask:0x5
	v_add_f32_dpp v58, v58, v58 row_half_mirror row_mask:0xf bank_mask:0xf bound_ctrl:1
	ds_read_b128 v[28:31], v76 offset:3840
	v_add_f32_dpp v72, v73, v73 row_half_mirror row_mask:0xf bank_mask:0xa
	v_add_f32_dpp v58, v58, v58 row_mirror row_mask:0xf bank_mask:0xf bound_ctrl:1
	s_waitcnt lgkmcnt(9)
	v_pk_fma_f32 v[4:5], v[58:59], v[36:37], v[60:61] op_sel_hi:[0,1,1]
	v_pk_fma_f32 v[6:7], v[58:59], v[38:39], v[62:63] op_sel_hi:[0,1,1]
	ds_read_b128 v[36:39], v76 offset:12032
	s_waitcnt lgkmcnt(7)
	v_pk_mul_f32 v[56:57], v[4:5], v[12:13]
	v_pk_mul_f32 v[64:65], v[4:5], v[40:41]
	v_pk_fma_f32 v[56:57], v[6:7], v[14:15], v[56:57]
	v_pk_fma_f32 v[64:65], v[6:7], v[42:43], v[64:65]
	ds_read_b128 v[40:43], v76 offset:16128
	v_add_f32_e32 v58, v56, v57
	v_pk_mul_f32 v[60:61], v[54:55], v[24:25] op_sel_hi:[0,1]
	v_pk_mul_f32 v[62:63], v[54:55], v[26:27] op_sel_hi:[0,1]
	v_add_f32_dpp v58, v58, v58 quad_perm:[1,0,3,2] row_mask:0xf bank_mask:0xf bound_ctrl:1
	v_add_f32_e32 v67, v64, v65
	s_nop 0
	v_add_f32_dpp v58, v58, v58 quad_perm:[2,3,0,1] row_mask:0xf bank_mask:0xf bound_ctrl:1
	s_waitcnt lgkmcnt(7)
	v_pk_fma_f32 v[60:61], v[4:5], v[8:9], v[60:61]
	v_pk_fma_f32 v[62:63], v[6:7], v[10:11], v[62:63]
	v_add_f32_dpp v74, v66, v66 row_mirror row_mask:0xf bank_mask:0x3
	v_add_f32_dpp v58, v58, v58 row_half_mirror row_mask:0xf bank_mask:0xf bound_ctrl:1
	s_nop 0
	v_add_f32_dpp v74, v67, v67 row_mirror row_mask:0xf bank_mask:0xc
	v_add_f32_dpp v58, v58, v58 row_mirror row_mask:0xf bank_mask:0xf bound_ctrl:1
	s_waitcnt lgkmcnt(6)
	v_pk_fma_f32 v[4:5], v[58:59], v[16:17], v[60:61] op_sel_hi:[0,1,1]
	v_pk_fma_f32 v[6:7], v[58:59], v[18:19], v[62:63] op_sel_hi:[0,1,1]
	s_waitcnt lgkmcnt(3)
	v_pk_mul_f32 v[56:57], v[4:5], v[32:33]
	v_pk_mul_f32 v[64:65], v[4:5], v[20:21]
	v_pk_fma_f32 v[56:57], v[6:7], v[34:35], v[56:57]
	v_pk_fma_f32 v[64:65], v[6:7], v[22:23], v[64:65]
	v_add_f32_e32 v58, v56, v57
	v_pk_mul_f32 v[60:61], v[54:55], v[44:45] op_sel:[1,0] op_sel_hi:[1,1]
	v_pk_mul_f32 v[62:63], v[54:55], v[46:47] op_sel:[1,0] op_sel_hi:[1,1]
	v_add_f32_dpp v58, v58, v58 quad_perm:[1,0,3,2] row_mask:0xf bank_mask:0xf bound_ctrl:1
	v_add_f32_e32 v66, v64, v65
	s_nop 0
	v_add_f32_dpp v58, v58, v58 quad_perm:[2,3,0,1] row_mask:0xf bank_mask:0xf bound_ctrl:1
	s_waitcnt lgkmcnt(2)
	v_pk_fma_f32 v[60:61], v[4:5], v[28:29], v[60:61]
	v_pk_fma_f32 v[62:63], v[6:7], v[30:31], v[62:63]
	v_add_f32_dpp v58, v58, v58 row_half_mirror row_mask:0xf bank_mask:0xf bound_ctrl:1
	s_nop 1
	v_add_f32_dpp v58, v58, v58 row_mirror row_mask:0xf bank_mask:0xf bound_ctrl:1
	s_waitcnt lgkmcnt(1)
	v_pk_fma_f32 v[4:5], v[58:59], v[36:37], v[60:61] op_sel_hi:[0,1,1]
	v_pk_fma_f32 v[6:7], v[58:59], v[38:39], v[62:63] op_sel_hi:[0,1,1]
	s_waitcnt lgkmcnt(0)
	v_pk_mul_f32 v[64:65], v[4:5], v[40:41]
	v_pk_fma_f32 v[64:65], v[6:7], v[42:43], v[64:65]
	v_add_f32_e32 v67, v64, v65
	s_cmp_lg_u32 s22, 0
	s_cbranch_scc1 .Lscan_w6A
	s_waitcnt vmcnt(0)
	s_branch .Lscan_wdA

; DI void scan_task(const Params& p, int l, int isP, int b, int h, int rg, char* smem, const bool dry) {
;     ...
; #pragma unroll
;     for (int s = 0; s < 32; s++) {
;       f32x4 w4n = w4, a4n = a4, b4n = b4;
;       uint2 urn = ur, ukn = uk;
;       float vn = v;
;       if (s < 31) {
;         w4n = *(const f32x4*)(fw + (s + 1) * 64);
;         a4n = *(const f32x4*)(fa + (s + 1) * 64);
;         b4n = *(const f32x4*)(fb + (s + 1) * 64);
;         urn = *(const uint2*)(pr + (s + 1) * 128);
;         ukn = *(const uint2*)(pk + (s + 1) * 128);
;         vn = vb[(s + 1) * 16];
;       }
;       __builtin_amdgcn_sched_barrier(0);
;       const f32x2 klo = {__uint_as_float(uk.x << 16), __uint_as_float(uk.x & 0xFFFF0000u)};
;       const f32x2 khi = {__uint_as_float(uk.y << 16), __uint_as_float(uk.y & 0xFFFF0000u)};
;       const f32x2 rlo = {__uint_as_float(ur.x << 16), __uint_as_float(ur.x & 0xFFFF0000u)};
;       const f32x2 rhi = {__uint_as_float(ur.y << 16), __uint_as_float(ur.y & 0xFFFF0000u)};
;       const f32x2 vv = {v, v};
;       const f32x2 t = Sa * a4.lo + Sb * a4.hi;
;       const f32x2 na = Sa * w4.lo + vv * klo;
;       const f32x2 nb = Sb * w4.hi + vv * khi;
;       float sa = t.x + t.y;
;       float yp = yprev;
;       rowsum16x2(sa, yp);
;       if (s >= 1 && s <= 16) ykeep0 = (jq == s - 1) ? yp : ykeep0;
;       if (s >= 17) ykeep1 = (jq == s - 17) ? yp : ykeep1;
;       const f32x2 sv = {sa, sa};
;       Sa = na + sv * b4.lo;
;       Sb = nb + sv * b4.hi;
;       const f32x2 yy = Sa * rlo + Sb * rhi;
;       yprev = yy.x + yy.y;
;       w4 = w4n; a4 = a4n; b4 = b4n; ur = urn; uk = ukn; v = vn;
;     }
.Lscan_noldB:
	s_waitcnt lgkmcnt(8)
	v_pk_mul_f32 v[56:57], v[4:5], v[12:13]
	v_pk_fma_f32 v[56:57], v[6:7], v[14:15], v[56:57]
	ds_read_b128 v[12:15], v76 offset:26112
	v_add_f32_e32 v58, v56, v57
	v_pk_mul_f32 v[60:61], v[48:49], v[24:25] op_sel_hi:[0,1]
	v_pk_mul_f32 v[62:63], v[48:49], v[26:27] op_sel_hi:[0,1]
	v_add_f32_dpp v58, v58, v58 quad_perm:[1,0,3,2] row_mask:0xf bank_mask:0xf bound_ctrl:1
	ds_read_b128 v[24:27], v76 offset:38400
	s_nop 0
	v_add_f32_dpp v58, v58, v58 quad_perm:[2,3,0,1] row_mask:0xf bank_mask:0xf bound_ctrl:1
	s_waitcnt lgkmcnt(9)
	v_pk_fma_f32 v[60:61], v[4:5], v[8:9], v[60:61]
	v_pk_fma_f32 v[62:63], v[6:7], v[10:11], v[62:63]
	v_add_f32_dpp v58, v58, v58 row_half_mirror row_mask:0xf bank_mask:0xf bound_ctrl:1
	ds_read_b128 v[8:11], v76 offset:22016
	s_nop 0
	v_add_f32_dpp v58, v58, v58 row_mirror row_mask:0xf bank_mask:0xf bound_ctrl:1
	s_waitcnt lgkmcnt(9)
	v_pk_fma_f32 v[4:5], v[58:59], v[16:17], v[60:61] op_sel_hi:[0,1,1]
	v_pk_fma_f32 v[6:7], v[58:59], v[18:19], v[62:63] op_sel_hi:[0,1,1]
	ds_read_b128 v[16:19], v76 offset:30208
	s_waitcnt lgkmcnt(7)
	v_pk_mul_f32 v[56:57], v[4:5], v[32:33]
	v_pk_mul_f32 v[64:65], v[4:5], v[20:21]
	v_pk_fma_f32 v[56:57], v[6:7], v[34:35], v[56:57]
	ds_read_b128 v[32:35], v76 offset:26368
	v_pk_fma_f32 v[64:65], v[6:7], v[22:23], v[64:65]
	ds_read_b128 v[20:23], v76 offset:34304
	v_add_f32_e32 v58, v56, v57
	v_pk_mul_f32 v[60:61], v[48:49], v[44:45] op_sel:[1,0] op_sel_hi:[1,1]
	v_pk_mul_f32 v[62:63], v[48:49], v[46:47] op_sel:[1,0] op_sel_hi:[1,1]
	v_add_f32_dpp v58, v58, v58 quad_perm:[1,0,3,2] row_mask:0xf bank_mask:0xf bound_ctrl:1
	ds_read_b128 v[44:47], v76 offset:38656
	v_add_f32_e32 v66, v64, v65
	ds_read_b128 v[52:55], v77 offset:42000
	v_add_f32_dpp v58, v58, v58 quad_perm:[2,3,0,1] row_mask:0xf bank_mask:0xf bound_ctrl:1
	s_waitcnt lgkmcnt(10)
	v_pk_fma_f32 v[60:61], v[4:5], v[28:29], v[60:61]
	v_pk_fma_f32 v[62:63], v[6:7], v[30:31], v[62:63]
	v_add_f32_dpp v58, v58, v58 row_half_mirror row_mask:0xf bank_mask:0xf bound_ctrl:1
	ds_read_b128 v[28:31], v76 offset:22272
	s_nop 0
	v_add_f32_dpp v58, v58, v58 row_mirror row_mask:0xf bank_mask:0xf bound_ctrl:1
	s_waitcnt lgkmcnt(10)
	v_pk_fma_f32 v[4:5], v[58:59], v[36:37], v[60:61] op_sel_hi:[0,1,1]
	v_pk_fma_f32 v[6:7], v[58:59], v[38:39], v[62:63] op_sel_hi:[0,1,1]
	ds_read_b128 v[36:39], v76 offset:30464
	s_waitcnt lgkmcnt(8)
	v_pk_mul_f32 v[56:57], v[4:5], v[12:13]
	v_pk_mul_f32 v[64:65], v[4:5], v[40:41]
	v_pk_fma_f32 v[56:57], v[6:7], v[14:15], v[56:57]
	ds_read_b128 v[12:15], v76 offset:26624
	v_pk_fma_f32 v[64:65], v[6:7], v[42:43], v[64:65]
	ds_read_b128 v[40:43], v76 offset:34560
	v_add_f32_e32 v58, v56, v57
	v_pk_mul_f32 v[60:61], v[50:51], v[24:25] op_sel_hi:[0,1]
	v_pk_mul_f32 v[62:63], v[50:51], v[26:27] op_sel_hi:[0,1]
	v_add_f32_dpp v58, v58, v58 quad_perm:[1,0,3,2] row_mask:0xf bank_mask:0xf bound_ctrl:1
	ds_read_b128 v[24:27], v76 offset:38912
	v_add_f32_e32 v67, v64, v65
	v_add_f32_dpp v58, v58, v58 quad_perm:[2,3,0,1] row_mask:0xf bank_mask:0xf bound_ctrl:1
	s_waitcnt lgkmcnt(10)
	v_pk_fma_f32 v[60:61], v[4:5], v[8:9], v[60:61]
	v_pk_fma_f32 v[62:63], v[6:7], v[10:11], v[62:63]
	v_add_f32_dpp v68, v66, v66 row_mirror row_mask:0xf bank_mask:0x3
	v_add_f32_dpp v58, v58, v58 row_half_mirror row_mask:0xf bank_mask:0xf bound_ctrl:1
	ds_read_b128 v[8:11], v76 offset:22528
	v_add_f32_dpp v68, v67, v67 row_mirror row_mask:0xf bank_mask:0xc
	v_add_f32_dpp v58, v58, v58 row_mirror row_mask:0xf bank_mask:0xf bound_ctrl:1
	s_waitcnt lgkmcnt(10)
	v_pk_fma_f32 v[4:5], v[58:59], v[16:17], v[60:61] op_sel_hi:[0,1,1]
	v_pk_fma_f32 v[6:7], v[58:59], v[18:19], v[62:63] op_sel_hi:[0,1,1]
	ds_read_b128 v[16:19], v76 offset:30720
	s_waitcnt lgkmcnt(8)
	v_pk_mul_f32 v[56:57], v[4:5], v[32:33]
	v_pk_mul_f32 v[64:65], v[4:5], v[20:21]
	v_pk_fma_f32 v[56:57], v[6:7], v[34:35], v[56:57]
	ds_read_b128 v[32:35], v76 offset:26880
	v_pk_fma_f32 v[64:65], v[6:7], v[22:23], v[64:65]
	ds_read_b128 v[20:23], v76 offset:34816
	v_add_f32_e32 v58, v56, v57
	v_pk_mul_f32 v[60:61], v[50:51], v[44:45] op_sel:[1,0] op_sel_hi:[1,1]
	v_pk_mul_f32 v[62:63], v[50:51], v[46:47] op_sel:[1,0] op_sel_hi:[1,1]
	v_add_f32_dpp v58, v58, v58 quad_perm:[1,0,3,2] row_mask:0xf bank_mask:0xf bound_ctrl:1
	ds_read_b128 v[44:47], v76 offset:39168
	v_add_f32_e32 v66, v64, v65
	v_add_f32_dpp v58, v58, v58 quad_perm:[2,3,0,1] row_mask:0xf bank_mask:0xf bound_ctrl:1
	s_waitcnt lgkmcnt(9)
	v_pk_fma_f32 v[60:61], v[4:5], v[28:29], v[60:61]
	v_pk_fma_f32 v[62:63], v[6:7], v[30:31], v[62:63]
	v_add_f32_dpp v58, v58, v58 row_half_mirror row_mask:0xf bank_mask:0xf bound_ctrl:1
	ds_read_b128 v[28:31], v76 offset:22784
	s_nop 0
	v_add_f32_dpp v58, v58, v58 row_mirror row_mask:0xf bank_mask:0xf bound_ctrl:1
	s_waitcnt lgkmcnt(9)
	v_pk_fma_f32 v[4:5], v[58:59], v[36:37], v[60:61] op_sel_hi:[0,1,1]
	v_pk_fma_f32 v[6:7], v[58:59], v[38:39], v[62:63] op_sel_hi:[0,1,1]
	ds_read_b128 v[36:39], v76 offset:30976
	s_waitcnt lgkmcnt(7)
	v_pk_mul_f32 v[56:57], v[4:5], v[12:13]
	v_pk_mul_f32 v[64:65], v[4:5], v[40:41]
	v_pk_fma_f32 v[56:57], v[6:7], v[14:15], v[56:57]
	ds_read_b128 v[12:15], v76 offset:27136
	v_pk_fma_f32 v[64:65], v[6:7], v[42:43], v[64:65]
	ds_read_b128 v[40:43], v76 offset:35072
	v_add_f32_e32 v58, v56, v57
	v_pk_mul_f32 v[60:61], v[52:53], v[24:25] op_sel_hi:[0,1]
	v_pk_mul_f32 v[62:63], v[52:53], v[26:27] op_sel_hi:[0,1]
	v_add_f32_dpp v58, v58, v58 quad_perm:[1,0,3,2] row_mask:0xf bank_mask:0xf bound_ctrl:1
	ds_read_b128 v[24:27], v76 offset:39424
	v_add_f32_e32 v67, v64, v65
	v_add_f32_dpp v58, v58, v58 quad_perm:[2,3,0,1] row_mask:0xf bank_mask:0xf bound_ctrl:1
	s_waitcnt lgkmcnt(9)
; DI void scan_task(const Params& p, int l, int isP, int b, int h, int rg, char* smem, const bool dry) {
;     ...
; #pragma unroll
;     for (int s = 0; s < 32; s++) {
;       f32x4 w4n = w4, a4n = a4, b4n = b4;
;       uint2 urn = ur, ukn = uk;
;       float vn = v;
;       if (s < 31) {
;         w4n = *(const f32x4*)(fw + (s + 1) * 64);
;         a4n = *(const f32x4*)(fa + (s + 1) * 64);
;         b4n = *(const f32x4*)(fb + (s + 1) * 64);
;         urn = *(const uint2*)(pr + (s + 1) * 128);
;         ukn = *(const uint2*)(pk + (s + 1) * 128);
;         vn = vb[(s + 1) * 16];
;       }
;       __builtin_amdgcn_sched_barrier(0);
;       const f32x2 klo = {__uint_as_float(uk.x << 16), __uint_as_float(uk.x & 0xFFFF0000u)};
;       const f32x2 khi = {__uint_as_float(uk.y << 16), __uint_as_float(uk.y & 0xFFFF0000u)};
;       const f32x2 rlo = {__uint_as_float(ur.x << 16), __uint_as_float(ur.x & 0xFFFF0000u)};
;       const f32x2 rhi = {__uint_as_float(ur.y << 16), __uint_as_float(ur.y & 0xFFFF0000u)};
;       const f32x2 vv = {v, v};
;       const f32x2 t = Sa * a4.lo + Sb * a4.hi;
;       const f32x2 na = Sa * w4.lo + vv * klo;
;       const f32x2 nb = Sb * w4.hi + vv * khi;
;       float sa = t.x + t.y;
;       float yp = yprev;
;       rowsum16x2(sa, yp);
;       if (s >= 1 && s <= 16) ykeep0 = (jq == s - 1) ? yp : ykeep0;
;       if (s >= 17) ykeep1 = (jq == s - 17) ? yp : ykeep1;
;       const f32x2 sv = {sa, sa};
;       Sa = na + sv * b4.lo;
;       Sb = nb + sv * b4.hi;
;       const f32x2 yy = Sa * rlo + Sb * rhi;
;       yprev = yy.x + yy.y;
;       w4 = w4n; a4 = a4n; b4 = b4n; ur = urn; uk = ukn; v = vn;
;     }
	v_pk_fma_f32 v[60:61], v[4:5], v[8:9], v[60:61]
	v_pk_fma_f32 v[62:63], v[6:7], v[10:11], v[62:63]
	v_add_f32_dpp v69, v66, v66 row_mirror row_mask:0xf bank_mask:0x3
	v_add_f32_dpp v58, v58, v58 row_half_mirror row_mask:0xf bank_mask:0xf bound_ctrl:1
	ds_read_b128 v[8:11], v76 offset:23040
	v_add_f32_dpp v69, v67, v67 row_mirror row_mask:0xf bank_mask:0xc
	v_add_f32_dpp v58, v58, v58 row_mirror row_mask:0xf bank_mask:0xf bound_ctrl:1
	s_waitcnt lgkmcnt(9)
	v_pk_fma_f32 v[4:5], v[58:59], v[16:17], v[60:61] op_sel_hi:[0,1,1]
	v_pk_fma_f32 v[6:7], v[58:59], v[18:19], v[62:63] op_sel_hi:[0,1,1]
	ds_read_b128 v[16:19], v76 offset:31232
	s_waitcnt lgkmcnt(7)
	v_pk_mul_f32 v[56:57], v[4:5], v[32:33]
	v_pk_mul_f32 v[64:65], v[4:5], v[20:21]
	v_pk_fma_f32 v[56:57], v[6:7], v[34:35], v[56:57]
	ds_read_b128 v[32:35], v76 offset:27392
	v_pk_fma_f32 v[64:65], v[6:7], v[22:23], v[64:65]
	ds_read_b128 v[20:23], v76 offset:35328
	v_add_f32_e32 v58, v56, v57
	v_pk_mul_f32 v[60:61], v[52:53], v[44:45] op_sel:[1,0] op_sel_hi:[1,1]
	v_pk_mul_f32 v[62:63], v[52:53], v[46:47] op_sel:[1,0] op_sel_hi:[1,1]
	v_add_f32_dpp v58, v58, v58 quad_perm:[1,0,3,2] row_mask:0xf bank_mask:0xf bound_ctrl:1
	ds_read_b128 v[44:47], v76 offset:39680
	v_add_f32_e32 v66, v64, v65
	ds_read_b128 v[48:51], v77 offset:42016
	v_add_f32_dpp v58, v58, v58 quad_perm:[2,3,0,1] row_mask:0xf bank_mask:0xf bound_ctrl:1
	s_waitcnt lgkmcnt(10)
	v_pk_fma_f32 v[60:61], v[4:5], v[28:29], v[60:61]
	v_pk_fma_f32 v[62:63], v[6:7], v[30:31], v[62:63]
	v_add_f32_dpp v68, v68, v68 row_half_mirror row_mask:0xf bank_mask:0x5
	v_add_f32_dpp v58, v58, v58 row_half_mirror row_mask:0xf bank_mask:0xf bound_ctrl:1
	ds_read_b128 v[28:31], v76 offset:23296
	v_add_f32_dpp v68, v69, v69 row_half_mirror row_mask:0xf bank_mask:0xa
	v_add_f32_dpp v58, v58, v58 row_mirror row_mask:0xf bank_mask:0xf bound_ctrl:1
	s_waitcnt lgkmcnt(10)
	v_pk_fma_f32 v[4:5], v[58:59], v[36:37], v[60:61] op_sel_hi:[0,1,1]
	v_pk_fma_f32 v[6:7], v[58:59], v[38:39], v[62:63] op_sel_hi:[0,1,1]
	ds_read_b128 v[36:39], v76 offset:31488
	s_waitcnt lgkmcnt(8)
	v_pk_mul_f32 v[56:57], v[4:5], v[12:13]
	v_pk_mul_f32 v[64:65], v[4:5], v[40:41]
	v_pk_fma_f32 v[56:57], v[6:7], v[14:15], v[56:57]
	ds_read_b128 v[12:15], v76 offset:27648
	v_pk_fma_f32 v[64:65], v[6:7], v[42:43], v[64:65]
	ds_read_b128 v[40:43], v76 offset:35584
	v_add_f32_e32 v58, v56, v57
	v_pk_mul_f32 v[60:61], v[54:55], v[24:25] op_sel_hi:[0,1]
	v_pk_mul_f32 v[62:63], v[54:55], v[26:27] op_sel_hi:[0,1]
	v_add_f32_dpp v58, v58, v58 quad_perm:[1,0,3,2] row_mask:0xf bank_mask:0xf bound_ctrl:1
	ds_read_b128 v[24:27], v76 offset:39936
	v_add_f32_e32 v67, v64, v65
	v_add_f32_dpp v58, v58, v58 quad_perm:[2,3,0,1] row_mask:0xf bank_mask:0xf bound_ctrl:1
	s_waitcnt lgkmcnt(10)
	v_pk_fma_f32 v[60:61], v[4:5], v[8:9], v[60:61]
	v_pk_fma_f32 v[62:63], v[6:7], v[10:11], v[62:63]
	v_add_f32_dpp v70, v66, v66 row_mirror row_mask:0xf bank_mask:0x3
	v_add_f32_dpp v58, v58, v58 row_half_mirror row_mask:0xf bank_mask:0xf bound_ctrl:1
	ds_read_b128 v[8:11], v76 offset:23552
	v_add_f32_dpp v70, v67, v67 row_mirror row_mask:0xf bank_mask:0xc
	v_add_f32_dpp v58, v58, v58 row_mirror row_mask:0xf bank_mask:0xf bound_ctrl:1
	s_waitcnt lgkmcnt(10)
	v_pk_fma_f32 v[4:5], v[58:59], v[16:17], v[60:61] op_sel_hi:[0,1,1]
	v_pk_fma_f32 v[6:7], v[58:59], v[18:19], v[62:63] op_sel_hi:[0,1,1]
	ds_read_b128 v[16:19], v76 offset:31744
	s_waitcnt lgkmcnt(8)
	v_pk_mul_f32 v[56:57], v[4:5], v[32:33]
	v_pk_mul_f32 v[64:65], v[4:5], v[20:21]
	v_pk_fma_f32 v[56:57], v[6:7], v[34:35], v[56:57]
	ds_read_b128 v[32:35], v76 offset:27904
	v_pk_fma_f32 v[64:65], v[6:7], v[22:23], v[64:65]
	ds_read_b128 v[20:23], v76 offset:35840
	v_add_f32_e32 v58, v56, v57
	v_pk_mul_f32 v[60:61], v[54:55], v[44:45] op_sel:[1,0] op_sel_hi:[1,1]
	v_pk_mul_f32 v[62:63], v[54:55], v[46:47] op_sel:[1,0] op_sel_hi:[1,1]
	v_add_f32_dpp v58, v58, v58 quad_perm:[1,0,3,2] row_mask:0xf bank_mask:0xf bound_ctrl:1
	ds_read_b128 v[44:47], v76 offset:40192
	v_add_f32_e32 v66, v64, v65
	v_add_f32_dpp v58, v58, v58 quad_perm:[2,3,0,1] row_mask:0xf bank_mask:0xf bound_ctrl:1
	s_waitcnt lgkmcnt(9)
	v_pk_fma_f32 v[60:61], v[4:5], v[28:29], v[60:61]
	v_pk_fma_f32 v[62:63], v[6:7], v[30:31], v[62:63]
	v_add_f32_dpp v58, v58, v58 row_half_mirror row_mask:0xf bank_mask:0xf bound_ctrl:1
	ds_read_b128 v[28:31], v76 offset:23808
	s_nop 0
	v_add_f32_dpp v58, v58, v58 row_mirror row_mask:0xf bank_mask:0xf bound_ctrl:1
	s_waitcnt lgkmcnt(9)
	v_pk_fma_f32 v[4:5], v[58:59], v[36:37], v[60:61] op_sel_hi:[0,1,1]
	v_pk_fma_f32 v[6:7], v[58:59], v[38:39], v[62:63] op_sel_hi:[0,1,1]
	ds_read_b128 v[36:39], v76 offset:32000
	s_waitcnt lgkmcnt(7)
	v_pk_mul_f32 v[56:57], v[4:5], v[12:13]
	v_pk_mul_f32 v[64:65], v[4:5], v[40:41]
	v_pk_fma_f32 v[56:57], v[6:7], v[14:15], v[56:57]
	ds_read_b128 v[12:15], v76 offset:28160
	v_pk_fma_f32 v[64:65], v[6:7], v[42:43], v[64:65]
	ds_read_b128 v[40:43], v76 offset:36096
	v_add_f32_e32 v58, v56, v57
	v_pk_mul_f32 v[60:61], v[48:49], v[24:25] op_sel_hi:[0,1]
	v_pk_mul_f32 v[62:63], v[48:49], v[26:27] op_sel_hi:[0,1]
	v_add_f32_dpp v58, v58, v58 quad_perm:[1,0,3,2] row_mask:0xf bank_mask:0xf bound_ctrl:1
	ds_read_b128 v[24:27], v76 offset:40448
	v_add_f32_e32 v67, v64, v65
	v_add_f32_dpp v58, v58, v58 quad_perm:[2,3,0,1] row_mask:0xf bank_mask:0xf bound_ctrl:1
	s_waitcnt lgkmcnt(9)
	v_pk_fma_f32 v[60:61], v[4:5], v[8:9], v[60:61]
	v_pk_fma_f32 v[62:63], v[6:7], v[10:11], v[62:63]
	v_add_f32_dpp v71, v66, v66 row_mirror row_mask:0xf bank_mask:0x3
	v_add_f32_dpp v58, v58, v58 row_half_mirror row_mask:0xf bank_mask:0xf bound_ctrl:1
	ds_read_b128 v[8:11], v76 offset:24064
	v_add_f32_dpp v71, v67, v67 row_mirror row_mask:0xf bank_mask:0xc
	v_add_f32_dpp v58, v58, v58 row_mirror row_mask:0xf bank_mask:0xf bound_ctrl:1
	s_waitcnt lgkmcnt(9)
; DI void scan_task(const Params& p, int l, int isP, int b, int h, int rg, char* smem, const bool dry) {
;     ...
;     for (int s = 0; s < 32; s++) {
;       f32x4 w4n = w4, a4n = a4, b4n = b4;
;       uint2 urn = ur, ukn = uk;
;       float vn = v;
;       if (s < 31) {
;         w4n = *(const f32x4*)(fw + (s + 1) * 64);
;         a4n = *(const f32x4*)(fa + (s + 1) * 64);
;         b4n = *(const f32x4*)(fb + (s + 1) * 64);
;         urn = *(const uint2*)(pr + (s + 1) * 128);
;         ukn = *(const uint2*)(pk + (s + 1) * 128);
;         vn = vb[(s + 1) * 16];
;       }
;       __builtin_amdgcn_sched_barrier(0);
;       const f32x2 klo = {__uint_as_float(uk.x << 16), __uint_as_float(uk.x & 0xFFFF0000u)};
;       const f32x2 khi = {__uint_as_float(uk.y << 16), __uint_as_float(uk.y & 0xFFFF0000u)};
;       const f32x2 rlo = {__uint_as_float(ur.x << 16), __uint_as_float(ur.x & 0xFFFF0000u)};
;       const f32x2 rhi = {__uint_as_float(ur.y << 16), __uint_as_float(ur.y & 0xFFFF0000u)};
;       const f32x2 vv = {v, v};
;       const f32x2 t = Sa * a4.lo + Sb * a4.hi;
;       const f32x2 na = Sa * w4.lo + vv * klo;
;       const f32x2 nb = Sb * w4.hi + vv * khi;
;       float sa = t.x + t.y;
;       float yp = yprev;
;       rowsum16x2(sa, yp);
;       if (s >= 1 && s <= 16) ykeep0 = (jq == s - 1) ? yp : ykeep0;
;       if (s >= 17) ykeep1 = (jq == s - 17) ? yp : ykeep1;
;       const f32x2 sv = {sa, sa};
;       Sa = na + sv * b4.lo;
;       Sb = nb + sv * b4.hi;
;       const f32x2 yy = Sa * rlo + Sb * rhi;
;       yprev = yy.x + yy.y;
;       w4 = w4n; a4 = a4n; b4 = b4n; ur = urn; uk = ukn; v = vn;
;     }
	v_pk_fma_f32 v[4:5], v[58:59], v[16:17], v[60:61] op_sel_hi:[0,1,1]
	v_pk_fma_f32 v[6:7], v[58:59], v[18:19], v[62:63] op_sel_hi:[0,1,1]
	ds_read_b128 v[16:19], v76 offset:32256
	s_waitcnt lgkmcnt(7)
	v_pk_mul_f32 v[56:57], v[4:5], v[32:33]
	v_pk_mul_f32 v[64:65], v[4:5], v[20:21]
	v_pk_fma_f32 v[56:57], v[6:7], v[34:35], v[56:57]
	ds_read_b128 v[32:35], v76 offset:28416
	v_pk_fma_f32 v[64:65], v[6:7], v[22:23], v[64:65]
	ds_read_b128 v[20:23], v76 offset:36352
	v_add_f32_e32 v58, v56, v57
	v_pk_mul_f32 v[60:61], v[48:49], v[44:45] op_sel:[1,0] op_sel_hi:[1,1]
	v_pk_mul_f32 v[62:63], v[48:49], v[46:47] op_sel:[1,0] op_sel_hi:[1,1]
	v_add_f32_dpp v58, v58, v58 quad_perm:[1,0,3,2] row_mask:0xf bank_mask:0xf bound_ctrl:1
	ds_read_b128 v[44:47], v76 offset:40704
	v_add_f32_e32 v66, v64, v65
	ds_read_b128 v[52:55], v77 offset:42032
	v_add_f32_dpp v58, v58, v58 quad_perm:[2,3,0,1] row_mask:0xf bank_mask:0xf bound_ctrl:1
	s_waitcnt lgkmcnt(10)
	v_pk_fma_f32 v[60:61], v[4:5], v[28:29], v[60:61]
	v_pk_fma_f32 v[62:63], v[6:7], v[30:31], v[62:63]
	v_add_f32_dpp v70, v70, v70 row_half_mirror row_mask:0xf bank_mask:0x5
	v_add_f32_dpp v58, v58, v58 row_half_mirror row_mask:0xf bank_mask:0xf bound_ctrl:1
	ds_read_b128 v[28:31], v76 offset:24320
	v_add_f32_dpp v70, v71, v71 row_half_mirror row_mask:0xf bank_mask:0xa
	v_add_f32_dpp v58, v58, v58 row_mirror row_mask:0xf bank_mask:0xf bound_ctrl:1
	s_waitcnt lgkmcnt(10)
	v_pk_fma_f32 v[4:5], v[58:59], v[36:37], v[60:61] op_sel_hi:[0,1,1]
	v_pk_fma_f32 v[6:7], v[58:59], v[38:39], v[62:63] op_sel_hi:[0,1,1]
	ds_read_b128 v[36:39], v76 offset:32512
	s_waitcnt lgkmcnt(8)
	v_pk_mul_f32 v[56:57], v[4:5], v[12:13]
	v_pk_mul_f32 v[64:65], v[4:5], v[40:41]
	v_pk_fma_f32 v[56:57], v[6:7], v[14:15], v[56:57]
	ds_read_b128 v[12:15], v76 offset:28672
	v_pk_fma_f32 v[64:65], v[6:7], v[42:43], v[64:65]
	ds_read_b128 v[40:43], v76 offset:36608
	v_add_f32_e32 v58, v56, v57
	v_pk_mul_f32 v[60:61], v[50:51], v[24:25] op_sel_hi:[0,1]
	v_pk_mul_f32 v[62:63], v[50:51], v[26:27] op_sel_hi:[0,1]
	v_add_f32_dpp v58, v58, v58 quad_perm:[1,0,3,2] row_mask:0xf bank_mask:0xf bound_ctrl:1
	ds_read_b128 v[24:27], v76 offset:40960
	v_add_f32_e32 v67, v64, v65
	v_add_f32_dpp v58, v58, v58 quad_perm:[2,3,0,1] row_mask:0xf bank_mask:0xf bound_ctrl:1
	s_waitcnt lgkmcnt(10)
	v_pk_fma_f32 v[60:61], v[4:5], v[8:9], v[60:61]
	v_pk_fma_f32 v[62:63], v[6:7], v[10:11], v[62:63]
	v_add_f32_dpp v72, v66, v66 row_mirror row_mask:0xf bank_mask:0x3
	v_add_f32_dpp v58, v58, v58 row_half_mirror row_mask:0xf bank_mask:0xf bound_ctrl:1
	ds_read_b128 v[8:11], v76 offset:24576
	v_add_f32_dpp v72, v67, v67 row_mirror row_mask:0xf bank_mask:0xc
	v_add_f32_dpp v58, v58, v58 row_mirror row_mask:0xf bank_mask:0xf bound_ctrl:1
	s_waitcnt lgkmcnt(10)
	v_pk_fma_f32 v[4:5], v[58:59], v[16:17], v[60:61] op_sel_hi:[0,1,1]
	v_pk_fma_f32 v[6:7], v[58:59], v[18:19], v[62:63] op_sel_hi:[0,1,1]
	ds_read_b128 v[16:19], v76 offset:32768
	s_waitcnt lgkmcnt(8)
	v_pk_mul_f32 v[56:57], v[4:5], v[32:33]
	v_pk_mul_f32 v[64:65], v[4:5], v[20:21]
	v_pk_fma_f32 v[56:57], v[6:7], v[34:35], v[56:57]
	ds_read_b128 v[32:35], v76 offset:28928
	v_pk_fma_f32 v[64:65], v[6:7], v[22:23], v[64:65]
	ds_read_b128 v[20:23], v76 offset:36864
	v_add_f32_e32 v58, v56, v57
	v_pk_mul_f32 v[60:61], v[50:51], v[44:45] op_sel:[1,0] op_sel_hi:[1,1]
	v_pk_mul_f32 v[62:63], v[50:51], v[46:47] op_sel:[1,0] op_sel_hi:[1,1]
	v_add_f32_dpp v58, v58, v58 quad_perm:[1,0,3,2] row_mask:0xf bank_mask:0xf bound_ctrl:1
	ds_read_b128 v[44:47], v76 offset:41216
	v_add_f32_e32 v66, v64, v65
	v_add_f32_dpp v58, v58, v58 quad_perm:[2,3,0,1] row_mask:0xf bank_mask:0xf bound_ctrl:1
	s_waitcnt lgkmcnt(9)
	v_pk_fma_f32 v[60:61], v[4:5], v[28:29], v[60:61]
	v_pk_fma_f32 v[62:63], v[6:7], v[30:31], v[62:63]
	v_add_f32_dpp v58, v58, v58 row_half_mirror row_mask:0xf bank_mask:0xf bound_ctrl:1
	ds_read_b128 v[28:31], v76 offset:24832
	s_nop 0
	v_add_f32_dpp v58, v58, v58 row_mirror row_mask:0xf bank_mask:0xf bound_ctrl:1
	s_waitcnt lgkmcnt(9)
	v_pk_fma_f32 v[4:5], v[58:59], v[36:37], v[60:61] op_sel_hi:[0,1,1]
	v_pk_fma_f32 v[6:7], v[58:59], v[38:39], v[62:63] op_sel_hi:[0,1,1]
	ds_read_b128 v[36:39], v76 offset:33024
	s_waitcnt lgkmcnt(7)
	v_pk_mul_f32 v[56:57], v[4:5], v[12:13]
	v_pk_mul_f32 v[64:65], v[4:5], v[40:41]
	v_pk_fma_f32 v[56:57], v[6:7], v[14:15], v[56:57]
	ds_read_b128 v[12:15], v76 offset:29184
	v_pk_fma_f32 v[64:65], v[6:7], v[42:43], v[64:65]
	ds_read_b128 v[40:43], v76 offset:37120
	v_add_f32_e32 v58, v56, v57
	v_pk_mul_f32 v[60:61], v[52:53], v[24:25] op_sel_hi:[0,1]
	v_pk_mul_f32 v[62:63], v[52:53], v[26:27] op_sel_hi:[0,1]
	v_add_f32_dpp v58, v58, v58 quad_perm:[1,0,3,2] row_mask:0xf bank_mask:0xf bound_ctrl:1
	ds_read_b128 v[24:27], v76 offset:41472
	v_add_f32_e32 v67, v64, v65
	v_add_f32_dpp v58, v58, v58 quad_perm:[2,3,0,1] row_mask:0xf bank_mask:0xf bound_ctrl:1
	s_waitcnt lgkmcnt(9)
	v_pk_fma_f32 v[60:61], v[4:5], v[8:9], v[60:61]
	v_pk_fma_f32 v[62:63], v[6:7], v[10:11], v[62:63]
	v_add_f32_dpp v73, v66, v66 row_mirror row_mask:0xf bank_mask:0x3
	v_add_f32_dpp v58, v58, v58 row_half_mirror row_mask:0xf bank_mask:0xf bound_ctrl:1
	ds_read_b128 v[8:11], v76 offset:25088
	v_add_f32_dpp v73, v67, v67 row_mirror row_mask:0xf bank_mask:0xc
	v_add_f32_dpp v58, v58, v58 row_mirror row_mask:0xf bank_mask:0xf bound_ctrl:1
	s_waitcnt lgkmcnt(9)
; DI void scan_task(const Params& p, int l, int isP, int b, int h, int rg, char* smem, const bool dry) {
;     ...
;   auto sstore = [&](int bi) {
;     char* bb = smem + bi * BUFB;
;     *(float4*)(bb + (ds * 64 + dj * 4) * 4) = rd0;
;     *(float4*)(bb + ((16 + ds) * 64 + dj * 4) * 4) = rd1;
;     {
;       CVT8(qa, alo, ahi)
;       float* d = (float*)(bb + 8192) + lst * 64 + lch * 8;
;       *(float4*)d = alo; *(float4*)(d + 4) = ahi;
;     }
;     {
;       CVT8(qb, blo, bhi)
;       float* d = (float*)(bb + 16384) + lst * 64 + lch * 8;
;       *(float4*)d = blo; *(float4*)(d + 4) = bhi;
;     }
;     ...
;     for (int s = 0; s < 32; s++) {
;       f32x4 w4n = w4, a4n = a4, b4n = b4;
;       uint2 urn = ur, ukn = uk;
;       float vn = v;
;       if (s < 31) {
;         w4n = *(const f32x4*)(fw + (s + 1) * 64);
;         a4n = *(const f32x4*)(fa + (s + 1) * 64);
;         b4n = *(const f32x4*)(fb + (s + 1) * 64);
;         urn = *(const uint2*)(pr + (s + 1) * 128);
;         ukn = *(const uint2*)(pk + (s + 1) * 128);
;         vn = vb[(s + 1) * 16];
;       }
;       __builtin_amdgcn_sched_barrier(0);
;       const f32x2 klo = {__uint_as_float(uk.x << 16), __uint_as_float(uk.x & 0xFFFF0000u)};
;       const f32x2 khi = {__uint_as_float(uk.y << 16), __uint_as_float(uk.y & 0xFFFF0000u)};
;       const f32x2 rlo = {__uint_as_float(ur.x << 16), __uint_as_float(ur.x & 0xFFFF0000u)};
;       const f32x2 rhi = {__uint_as_float(ur.y << 16), __uint_as_float(ur.y & 0xFFFF0000u)};
;       const f32x2 vv = {v, v};
;       const f32x2 t = Sa * a4.lo + Sb * a4.hi;
;       const f32x2 na = Sa * w4.lo + vv * klo;
;       const f32x2 nb = Sb * w4.hi + vv * khi;
;       float sa = t.x + t.y;
;       float yp = yprev;
;       rowsum16x2(sa, yp);
;       if (s >= 1 && s <= 16) ykeep0 = (jq == s - 1) ? yp : ykeep0;
;       if (s >= 17) ykeep1 = (jq == s - 17) ? yp : ykeep1;
;       const f32x2 sv = {sa, sa};
;       Sa = na + sv * b4.lo;
;       Sb = nb + sv * b4.hi;
;       const f32x2 yy = Sa * rlo + Sb * rhi;
;       yprev = yy.x + yy.y;
;       w4 = w4n; a4 = a4n; b4 = b4n; ur = urn; uk = ukn; v = vn;
;     }
;     {
;       const float yl = rowsum16(yprev);
;       ykeep1 = (jq == 15) ? yl : ykeep1;
;     }
;     if (!dry) { yo[0] = ykeep0; yo[(size_t)16 * 512] = ykeep1; }
;     if (more) sstore((c + 1) & 1);
;     __syncthreads();
	v_pk_fma_f32 v[4:5], v[58:59], v[16:17], v[60:61] op_sel_hi:[0,1,1]
	v_pk_fma_f32 v[6:7], v[58:59], v[18:19], v[62:63] op_sel_hi:[0,1,1]
	ds_read_b128 v[16:19], v76 offset:33280
	s_waitcnt lgkmcnt(7)
	v_pk_mul_f32 v[56:57], v[4:5], v[32:33]
	v_pk_mul_f32 v[64:65], v[4:5], v[20:21]
	v_pk_fma_f32 v[56:57], v[6:7], v[34:35], v[56:57]
	ds_read_b128 v[32:35], v76 offset:29440
	v_pk_fma_f32 v[64:65], v[6:7], v[22:23], v[64:65]
	ds_read_b128 v[20:23], v76 offset:37376
	v_add_f32_e32 v58, v56, v57
	v_pk_mul_f32 v[60:61], v[52:53], v[44:45] op_sel:[1,0] op_sel_hi:[1,1]
	v_pk_mul_f32 v[62:63], v[52:53], v[46:47] op_sel:[1,0] op_sel_hi:[1,1]
	v_add_f32_dpp v58, v58, v58 quad_perm:[1,0,3,2] row_mask:0xf bank_mask:0xf bound_ctrl:1
	ds_read_b128 v[44:47], v76 offset:41728
	v_add_f32_e32 v66, v64, v65
	v_add_f32_dpp v58, v58, v58 quad_perm:[2,3,0,1] row_mask:0xf bank_mask:0xf bound_ctrl:1
	s_waitcnt lgkmcnt(9)
	v_pk_fma_f32 v[60:61], v[4:5], v[28:29], v[60:61]
	v_pk_fma_f32 v[62:63], v[6:7], v[30:31], v[62:63]
	v_add_f32_dpp v72, v72, v72 row_half_mirror row_mask:0xf bank_mask:0x5
	v_add_f32_dpp v58, v58, v58 row_half_mirror row_mask:0xf bank_mask:0xf bound_ctrl:1
	ds_read_b128 v[28:31], v76 offset:25344
	v_add_f32_dpp v72, v73, v73 row_half_mirror row_mask:0xf bank_mask:0xa
	v_add_f32_dpp v58, v58, v58 row_mirror row_mask:0xf bank_mask:0xf bound_ctrl:1
	s_waitcnt lgkmcnt(9)
	v_pk_fma_f32 v[4:5], v[58:59], v[36:37], v[60:61] op_sel_hi:[0,1,1]
	v_pk_fma_f32 v[6:7], v[58:59], v[38:39], v[62:63] op_sel_hi:[0,1,1]
	ds_read_b128 v[36:39], v76 offset:33536
	s_waitcnt lgkmcnt(7)
	v_pk_mul_f32 v[56:57], v[4:5], v[12:13]
	v_pk_mul_f32 v[64:65], v[4:5], v[40:41]
	v_pk_fma_f32 v[56:57], v[6:7], v[14:15], v[56:57]
	v_pk_fma_f32 v[64:65], v[6:7], v[42:43], v[64:65]
	ds_read_b128 v[40:43], v76 offset:37632
	v_add_f32_e32 v58, v56, v57
	v_pk_mul_f32 v[60:61], v[54:55], v[24:25] op_sel_hi:[0,1]
	v_pk_mul_f32 v[62:63], v[54:55], v[26:27] op_sel_hi:[0,1]
	v_add_f32_dpp v58, v58, v58 quad_perm:[1,0,3,2] row_mask:0xf bank_mask:0xf bound_ctrl:1
	v_add_f32_e32 v67, v64, v65
	s_nop 0
	v_add_f32_dpp v58, v58, v58 quad_perm:[2,3,0,1] row_mask:0xf bank_mask:0xf bound_ctrl:1
	s_waitcnt lgkmcnt(7)
	v_pk_fma_f32 v[60:61], v[4:5], v[8:9], v[60:61]
	v_pk_fma_f32 v[62:63], v[6:7], v[10:11], v[62:63]
	v_add_f32_dpp v74, v66, v66 row_mirror row_mask:0xf bank_mask:0x3
	v_add_f32_dpp v58, v58, v58 row_half_mirror row_mask:0xf bank_mask:0xf bound_ctrl:1
	s_nop 0
	v_add_f32_dpp v74, v67, v67 row_mirror row_mask:0xf bank_mask:0xc
	v_add_f32_dpp v58, v58, v58 row_mirror row_mask:0xf bank_mask:0xf bound_ctrl:1
	s_waitcnt lgkmcnt(6)
	v_pk_fma_f32 v[4:5], v[58:59], v[16:17], v[60:61] op_sel_hi:[0,1,1]
	v_pk_fma_f32 v[6:7], v[58:59], v[18:19], v[62:63] op_sel_hi:[0,1,1]
	s_waitcnt lgkmcnt(3)
	v_pk_mul_f32 v[56:57], v[4:5], v[32:33]
	v_pk_mul_f32 v[64:65], v[4:5], v[20:21]
	v_pk_fma_f32 v[56:57], v[6:7], v[34:35], v[56:57]
	v_pk_fma_f32 v[64:65], v[6:7], v[22:23], v[64:65]
	v_add_f32_e32 v58, v56, v57
	v_pk_mul_f32 v[60:61], v[54:55], v[44:45] op_sel:[1,0] op_sel_hi:[1,1]
	v_pk_mul_f32 v[62:63], v[54:55], v[46:47] op_sel:[1,0] op_sel_hi:[1,1]
	v_add_f32_dpp v58, v58, v58 quad_perm:[1,0,3,2] row_mask:0xf bank_mask:0xf bound_ctrl:1
	v_add_f32_e32 v66, v64, v65
	s_nop 0
	v_add_f32_dpp v58, v58, v58 quad_perm:[2,3,0,1] row_mask:0xf bank_mask:0xf bound_ctrl:1
	s_waitcnt lgkmcnt(2)
	v_pk_fma_f32 v[60:61], v[4:5], v[28:29], v[60:61]
	v_pk_fma_f32 v[62:63], v[6:7], v[30:31], v[62:63]
	v_add_f32_dpp v58, v58, v58 row_half_mirror row_mask:0xf bank_mask:0xf bound_ctrl:1
	s_nop 1
	v_add_f32_dpp v58, v58, v58 row_mirror row_mask:0xf bank_mask:0xf bound_ctrl:1
	s_waitcnt lgkmcnt(1)
	v_pk_fma_f32 v[4:5], v[58:59], v[36:37], v[60:61] op_sel_hi:[0,1,1]
	v_pk_fma_f32 v[6:7], v[58:59], v[38:39], v[62:63] op_sel_hi:[0,1,1]
	s_waitcnt lgkmcnt(0)
	v_pk_mul_f32 v[64:65], v[4:5], v[40:41]
	v_pk_fma_f32 v[64:65], v[6:7], v[42:43], v[64:65]
	v_add_f32_e32 v67, v64, v65
	s_cmp_lg_u32 s22, 0
	s_cbranch_scc0 .Lscan_lastB
	s_waitcnt vmcnt(6)
	ds_write_b128 v78, v[84:87] offset:0
	v_lshlrev_b32_e32 v8, 16, v92
	v_and_b32_e32 v9, 0xffff0000, v92
	v_lshlrev_b32_e32 v10, 16, v93
	v_and_b32_e32 v11, 0xffff0000, v93
	ds_write_b128 v78, v[8:11] offset:4096
	v_lshlrev_b32_e32 v12, 16, v94
	v_and_b32_e32 v13, 0xffff0000, v94
	v_lshlrev_b32_e32 v14, 16, v95
	v_and_b32_e32 v15, 0xffff0000, v95
	ds_write_b128 v78, v[12:15] offset:8192
	v_lshlrev_b32_e32 v16, 16, v88
	v_and_b32_e32 v17, 0xffff0000, v88
	v_lshlrev_b32_e32 v18, 16, v89
	v_and_b32_e32 v19, 0xffff0000, v89
	ds_write_b128 v78, v[16:19] offset:12288
	v_lshlrev_b32_e32 v20, 16, v90
	v_and_b32_e32 v21, 0xffff0000, v90
	v_lshlrev_b32_e32 v22, 16, v91
	v_and_b32_e32 v23, 0xffff0000, v91
	ds_write_b128 v78, v[20:23] offset:16384
	v_lshlrev_b32_e32 v24, 16, v96
	ds_write_b32 v79, v24 offset:20480
	s_waitcnt lgkmcnt(0)
	s_barrier
	ds_read_b128 v[12:15], v76 offset:4096
	ds_read_b128 v[24:27], v76 offset:16384
	ds_read_b128 v[48:51], v77 offset:20480
	ds_read_b128 v[8:11], v76 offset:0
	ds_read_b128 v[16:19], v76 offset:8192
	ds_read_b128 v[20:23], v76 offset:12288
	ds_read_b128 v[32:35], v76 offset:4352
	ds_read_b128 v[44:47], v76 offset:16640
	ds_read_b128 v[28:31], v76 offset:256
	ds_read_b128 v[36:39], v76 offset:8448
	ds_read_b128 v[40:43], v76 offset:12544
	s_branch .Lscan_tailB
